# v_s2 + persistent -Mref splat block for attention QK C operand (17 fewer VALU per tile)
# speedup vs baseline: 1.0059x; 1.0059x over previous
.LBB0_994:
	s_mov_b32 s6, m0
	s_mov_b32 m0, s63
	s_nop 0
	global_load_lds_dwordx4 v211, s[14:15]
	s_mov_b32 m0, s6
	s_add_i32 s6, s63, 0x2000
	s_mov_b32 s7, m0
	s_mov_b32 m0, s6
	s_nop 0
	global_load_lds_dwordx4 v211, s[18:19]
	s_mov_b32 m0, s7
	s_mov_b32 s6, m0
	s_mov_b32 m0, s68
	s_nop 0
	global_load_lds_dwordx4 v212, s[16:17]
	s_mov_b32 m0, s6
	v_mov_b32_e32 v128, 0x3f803f80
	s_add_i32 s6, s63, 0x6000
	s_mov_b32 s7, m0
	s_mov_b32 m0, s6
	s_nop 0
	global_load_lds_dwordx4 v212, s[20:21]
	s_mov_b32 m0, s7
	s_waitcnt vmcnt(8) lgkmcnt(0)
	s_barrier
	v_add_u32_e32 v4, v215, v170
	ds_read_b128 v[0:3], v4 offset:4096
	ds_read_b128 v[4:7], v4
	v_add_u32_e32 v12, v215, v172
	v_add_u32_e32 v20, v215, v173
	v_add_u32_e32 v28, v215, v174
	v_mov_b32_e32 v226, v161
	ds_read_b128 v[8:11], v12
	ds_read_b128 v[16:19], v12 offset:4096
	ds_read_b128 v[12:15], v20
	ds_read_b128 v[20:23], v20 offset:4096
	ds_read_b128 v[24:27], v28
	ds_read_b128 v[28:31], v28 offset:4096
	s_nop 0
	v_mov_b32_e32 v227, v161
	v_mov_b32_e32 v228, v161
	v_mov_b32_e32 v229, v161
	v_mov_b32_e32 v230, v161
	v_mov_b32_e32 v231, v161
	v_mov_b32_e32 v232, v161
	v_mov_b32_e32 v233, v161
	v_mov_b32_e32 v234, v161
	v_mov_b32_e32 v235, v161
	v_mov_b32_e32 v236, v161
	v_mov_b32_e32 v237, v161
	v_mov_b32_e32 v238, v161
	v_mov_b32_e32 v239, v161
	v_mov_b32_e32 v240, v161
	v_mov_b32_e32 v241, v161
	s_waitcnt lgkmcnt(6)
	s_nop 0
	v_mfma_f32_32x32x16_bf16 v[96:111], v[4:7], v[112:115], v[226:241]
	v_mfma_f32_32x32x16_bf16 v[80:95], v[0:3], v[112:115], v[226:241]
	s_waitcnt lgkmcnt(5)
	v_mfma_f32_32x32x16_bf16 v[96:111], v[8:11], v[116:119], v[96:111]
	s_waitcnt lgkmcnt(3)
	v_mfma_f32_32x32x16_bf16 v[96:111], v[12:15], v[120:123], v[96:111]
	ds_read_b64_tr_b16 v[0:1], v175
	ds_read_b64_tr_b16 v[2:3], v176
	ds_read_b64_tr_b16 v[4:5], v177
	ds_read_b64_tr_b16 v[6:7], v178
	ds_read_b64_tr_b16 v[8:9], v179
	ds_read_b64_tr_b16 v[10:11], v180
	ds_read_b64_tr_b16 v[12:13], v181
	ds_read_b64_tr_b16 v[14:15], v182
	s_waitcnt lgkmcnt(9)
	v_mfma_f32_32x32x16_bf16 v[96:111], v[24:27], v[124:127], v[96:111]
	v_mfma_f32_32x32x16_bf16 v[80:95], v[16:19], v[116:119], v[80:95]
	s_cmp_lg_u32 s82, 0
	s_cselect_b64 s[40:41], -1, 0
	s_cmp_eq_u32 s82, 0
	v_mfma_f32_32x32x16_bf16 v[80:95], v[20:23], v[120:123], v[80:95]
	s_waitcnt lgkmcnt(8)
	v_mfma_f32_32x32x16_bf16 v[80:95], v[28:31], v[124:127], v[80:95]
	s_cbranch_scc1 .LBB0_996
	s_add_i32 s6, s63, 0x8000
	s_mov_b32 s7, m0
	s_mov_b32 m0, s6
	s_nop 0
	global_load_lds_dwordx4 v211, s[22:23]
	s_mov_b32 m0, s7

.LBB0_1009:
	v_add_u32_e32 v80, s87, v213
	v_add_u32_e32 v81, v80, v170
	ds_read_b128 v[132:135], v81
	ds_read_b128 v[136:139], v81 offset:4096
	v_add_u32_e32 v81, v80, v172
	ds_read_b128 v[140:143], v81
	ds_read_b128 v[148:151], v81 offset:4096
	v_add_u32_e32 v81, v80, v173
	v_add_u32_e32 v80, v80, v174
	ds_read_b128 v[144:147], v81
	ds_read_b128 v[152:155], v81 offset:4096
	ds_read_b128 v[216:219], v80
	ds_read_b128 v[220:223], v80 offset:4096
	v_add_u32_e32 v156, s87, v171
	s_waitcnt lgkmcnt(7)
	v_mfma_f32_32x32x16_bf16 v[96:111], v[132:135], v[112:115], v[226:241]
	s_waitcnt lgkmcnt(6)
	v_mfma_f32_32x32x16_bf16 v[80:95], v[136:139], v[112:115], v[226:241]
	s_waitcnt lgkmcnt(5)
	v_mfma_f32_32x32x16_bf16 v[96:111], v[140:143], v[116:119], v[96:111]
	s_waitcnt lgkmcnt(3)
	v_mfma_f32_32x32x16_bf16 v[96:111], v[144:147], v[120:123], v[96:111]
	ds_read_b64_tr_b16 v[144:145], v156 offset:16384
	ds_read_b64_tr_b16 v[146:147], v156 offset:16896
	ds_read_b64_tr_b16 v[140:141], v156 offset:20480
	ds_read_b64_tr_b16 v[142:143], v156 offset:20992
	ds_read_b64_tr_b16 v[136:137], v156 offset:24576
	ds_read_b64_tr_b16 v[138:139], v156 offset:25088
	ds_read_b64_tr_b16 v[132:133], v156 offset:28672
	ds_read_b64_tr_b16 v[134:135], v156 offset:29184
	s_waitcnt lgkmcnt(9)
	v_mfma_f32_32x32x16_bf16 v[96:111], v[216:219], v[124:127], v[96:111]
	v_mfma_f32_32x32x16_bf16 v[80:95], v[148:151], v[116:119], v[80:95]
	s_cmp_lt_u32 s85, s83
	s_cselect_b64 s[50:51], -1, 0
	s_cmp_ge_u32 s85, s83
	v_mfma_f32_32x32x16_bf16 v[80:95], v[152:155], v[120:123], v[80:95]
	s_waitcnt lgkmcnt(8)
	v_mfma_f32_32x32x16_bf16 v[80:95], v[220:223], v[124:127], v[80:95]
	s_cbranch_scc1 .LBB0_1011
	s_add_i32 s6, s86, s63
	s_mov_b32 s7, m0
	s_mov_b32 m0, s6
	s_nop 0
	global_load_lds_dwordx4 v211, s[48:49]
	s_mov_b32 m0, s7
